# global attention loop: LDS-DMA issue moved from the step head (next to the ds_read burst) into the QK phase VALU gaps; padded to keep hot-loop placement
# speedup vs baseline: 1.0127x; 1.0075x over previous
.Lgo_ks:
.Lgo_nk:
	s_add_i32 s96, s7, 1
	s_cmp_lt_i32 s96, s71
	s_cbranch_scc0 .Lgo_nv
	s_cmp_lg_u32 s96, 4
	s_cbranch_scc1 .Lgo_vs
	v_mad_i64_i32 v[246:247], s[80:81], s84, v215, v[200:201]
	v_ashrrev_i32_e32 v243, 31, v249
	v_mov_b32_e32 v242, v249
	v_lshl_add_u64 v[246:247], v[242:243], 0, v[246:247]
.Lgo_vs:
.Lgo_nv:
	s_add_i32 s72, s7, 2
	s_mul_hi_u32 s80, s72, 0x55555556
	s_mul_i32 s80, s80, 3
	s_sub_u32 s80, s72, s80
	s_lshl_b32 s81, s80, 13
	s_cmp_eq_u32 s80, 2
	s_cselect_b32 s81, 0x6000, s81
	v_add_u32_e32 v242, s81, v253
	s_add_i32 s72, s7, 1
	s_and_b32 s80, s72, 3
	s_lshl_b32 s81, s80, 13
	s_cmp_eq_u32 s80, 3
	s_cselect_b32 s81, 0xe000, s81
	v_add_u32_e32 v243, s81, v221
	ds_read_b64_tr_b16 v[160:161], v242 offset:24576
	ds_read_b64_tr_b16 v[162:163], v242 offset:25088
	ds_read_b64_tr_b16 v[164:165], v242 offset:25600
	ds_read_b64_tr_b16 v[166:167], v242 offset:26112
	ds_read_b64_tr_b16 v[168:169], v242 offset:26624
	ds_read_b64_tr_b16 v[170:171], v242 offset:27136
	ds_read_b64_tr_b16 v[172:173], v242 offset:27648
	ds_read_b64_tr_b16 v[174:175], v242 offset:28160
	v_mfma_f32_32x32x16_bf16 v[80:95], v[128:131], v[96:99], 0
	v_add_f32_e32 v204, v204, v32
	v_add_f32_e32 v205, v205, v33
	v_add_f32_e32 v208, v208, v34
	v_add_f32_e32 v209, v209, v35
	v_cvt_pk_bf16_f32 v112, v32, v33
	v_cvt_pk_bf16_f32 v113, v34, v35
	v_mfma_f32_32x32x16_bf16 v[48:63], v[132:135], v[96:99], 0
	v_add_f32_e32 v204, v204, v36
	v_add_f32_e32 v205, v205, v37
	v_add_f32_e32 v208, v208, v38
	v_add_f32_e32 v209, v209, v39
	v_cvt_pk_bf16_f32 v114, v36, v37
	v_cvt_pk_bf16_f32 v115, v38, v39
	s_and_b64 vcc, exec, s[82:83]
	s_cbranch_vccz .Lgo_mk
	s_add_i32 s96, s7, 3
	s_and_b32 s80, s96, 3
	s_lshl_b32 s81, s80, 13
	s_cmp_eq_u32 s80, 3
	s_cselect_b32 s81, 0xe000, s81
	s_add_i32 s81, s81, s100
	s_mov_b32 m0, s81
	s_nop 0
	global_load_lds_dwordx4 v[244:245], off
	v_lshl_add_u64 v[244:245], v[244:245], 0, s[98:99]
.Lgo_mk:
	v_mfma_f32_32x32x16_bf16 v[80:95], v[136:139], v[100:103], v[80:95]
	v_add_f32_e32 v204, v204, v40
	v_add_f32_e32 v205, v205, v41
	v_add_f32_e32 v208, v208, v42
	v_add_f32_e32 v209, v209, v43
	v_cvt_pk_bf16_f32 v116, v40, v41
	v_cvt_pk_bf16_f32 v117, v42, v43
	v_mfma_f32_32x32x16_bf16 v[48:63], v[140:143], v[100:103], v[48:63]
	v_add_f32_e32 v204, v204, v44
	v_add_f32_e32 v205, v205, v45
	v_add_f32_e32 v208, v208, v46
	v_add_f32_e32 v209, v209, v47
	v_cvt_pk_bf16_f32 v118, v44, v45
	v_cvt_pk_bf16_f32 v119, v46, v47
	v_mfma_f32_32x32x16_bf16 v[80:95], v[144:147], v[104:107], v[80:95]
	v_add_f32_e32 v204, v204, v64
	v_add_f32_e32 v205, v205, v65
	v_add_f32_e32 v208, v208, v66
	v_add_f32_e32 v209, v209, v67
	v_cvt_pk_bf16_f32 v120, v64, v65
	v_cvt_pk_bf16_f32 v121, v66, v67
	v_mfma_f32_32x32x16_bf16 v[48:63], v[148:151], v[104:107], v[48:63]
	v_add_f32_e32 v204, v204, v68
	v_add_f32_e32 v205, v205, v69
	v_add_f32_e32 v208, v208, v70
	v_add_f32_e32 v209, v209, v71
	v_cvt_pk_bf16_f32 v122, v68, v69
	v_cvt_pk_bf16_f32 v123, v70, v71
	s_add_i32 s96, s7, 1
	s_cmp_lt_i32 s96, s71
	s_cbranch_scc0 .Lgo_mv
	s_mul_hi_u32 s80, s96, 0x55555556
	s_mul_i32 s80, s80, 3
	s_sub_u32 s80, s96, s80
	s_lshl_b32 s81, s80, 13
	s_cmp_eq_u32 s80, 2
	s_cselect_b32 s81, 0x6000, s81
	s_add_i32 s81, s81, 0x6000
	s_add_i32 s81, s81, s100
	s_mov_b32 m0, s81
	s_nop 0
	global_load_lds_dwordx4 v[246:247], off
	v_lshl_add_u64 v[246:247], v[246:247], 0, s[98:99]
.Lgo_mv:
	v_mfma_f32_32x32x16_bf16 v[80:95], v[152:155], v[108:111], v[80:95]
	v_add_f32_e32 v204, v204, v72
	v_add_f32_e32 v205, v205, v73
	v_add_f32_e32 v208, v208, v74
	v_add_f32_e32 v209, v209, v75
	v_cvt_pk_bf16_f32 v124, v72, v73
	v_cvt_pk_bf16_f32 v125, v74, v75
	v_mfma_f32_32x32x16_bf16 v[48:63], v[156:159], v[108:111], v[48:63]
	v_add_f32_e32 v204, v204, v76
	v_add_f32_e32 v205, v205, v77
	v_add_f32_e32 v208, v208, v78
	v_add_f32_e32 v209, v209, v79
	v_cvt_pk_bf16_f32 v126, v76, v77
	v_cvt_pk_bf16_f32 v127, v78, v79
	ds_read_b64_tr_b16 v[176:177], v242 offset:28672
	ds_read_b64_tr_b16 v[178:179], v242 offset:29184
	ds_read_b64_tr_b16 v[180:181], v242 offset:29696
	ds_read_b64_tr_b16 v[182:183], v242 offset:30208
	ds_read_b64_tr_b16 v[184:185], v242 offset:30720
	ds_read_b64_tr_b16 v[186:187], v242 offset:31232
	ds_read_b64_tr_b16 v[188:189], v242 offset:31744
	s_waitcnt lgkmcnt(14)
	ds_read_b64_tr_b16 v[190:191], v242 offset:32256
	s_waitcnt lgkmcnt(14)
	v_mfma_f32_32x32x16_bf16 v[0:15], v[160:163], v[112:115], v[0:15]
	v_exp_f32_e32 v80, v80
	v_exp_f32_e32 v81, v81
	v_exp_f32_e32 v82, v82
	v_exp_f32_e32 v83, v83
	s_waitcnt lgkmcnt(12)
	v_mfma_f32_32x32x16_bf16 v[0:15], v[164:167], v[116:119], v[0:15]
	v_exp_f32_e32 v84, v84
	v_exp_f32_e32 v85, v85
	v_exp_f32_e32 v86, v86
	v_exp_f32_e32 v87, v87
	s_waitcnt lgkmcnt(10)
	v_mfma_f32_32x32x16_bf16 v[0:15], v[168:171], v[120:123], v[0:15]
	v_exp_f32_e32 v88, v88
	v_exp_f32_e32 v89, v89
	v_exp_f32_e32 v90, v90
	v_exp_f32_e32 v91, v91
	ds_read_b128 v[128:131], v243
	ds_read_b128 v[132:135], v243 offset:512
	s_waitcnt lgkmcnt(10)
	v_mfma_f32_32x32x16_bf16 v[0:15], v[172:175], v[124:127], v[0:15]
	v_exp_f32_e32 v92, v92
	v_exp_f32_e32 v93, v93
	v_exp_f32_e32 v94, v94
	v_exp_f32_e32 v95, v95
	ds_read_b128 v[136:139], v243 offset:2048
	ds_read_b128 v[140:143], v243 offset:2560
	s_waitcnt lgkmcnt(10)
	v_mfma_f32_32x32x16_bf16 v[16:31], v[176:179], v[112:115], v[16:31]
	v_exp_f32_e32 v48, v48
	v_exp_f32_e32 v49, v49
	v_exp_f32_e32 v50, v50
	v_exp_f32_e32 v51, v51
	ds_read_b128 v[144:147], v243 offset:4096
	ds_read_b128 v[148:151], v243 offset:4608
	s_waitcnt lgkmcnt(10)
	v_mfma_f32_32x32x16_bf16 v[16:31], v[180:183], v[116:119], v[16:31]
	v_exp_f32_e32 v52, v52
	v_exp_f32_e32 v53, v53
	v_exp_f32_e32 v54, v54
	v_exp_f32_e32 v55, v55
	ds_read_b128 v[152:155], v243 offset:6144
	ds_read_b128 v[156:159], v243 offset:6656
	s_waitcnt lgkmcnt(10)
	v_mfma_f32_32x32x16_bf16 v[16:31], v[184:187], v[120:123], v[16:31]
	v_exp_f32_e32 v56, v56
	v_exp_f32_e32 v57, v57
	v_exp_f32_e32 v58, v58
	v_exp_f32_e32 v59, v59
	s_waitcnt lgkmcnt(8)
	v_mfma_f32_32x32x16_bf16 v[16:31], v[188:191], v[124:127], v[16:31]
	v_exp_f32_e32 v60, v60
	v_exp_f32_e32 v61, v61
	v_exp_f32_e32 v62, v62
	v_exp_f32_e32 v63, v63
	s_waitcnt lgkmcnt(0)
	s_and_b64 vcc, exec, s[82:83]
	s_cbranch_vccz .Lgo_w0
	s_waitcnt vmcnt(2)
	s_branch .Lgo_w1

.Lge_vs:
.Lge_nv:
	s_add_i32 s72, s7, 2
	s_mul_hi_u32 s80, s72, 0x55555556
	s_mul_i32 s80, s80, 3
	s_sub_u32 s80, s72, s80
	s_lshl_b32 s81, s80, 13
	s_cmp_eq_u32 s80, 2
	s_cselect_b32 s81, 0x6000, s81
	v_add_u32_e32 v242, s81, v253
	s_add_i32 s72, s7, 1
	s_and_b32 s80, s72, 3
	s_lshl_b32 s81, s80, 13
	s_cmp_eq_u32 s80, 3
	s_cselect_b32 s81, 0xe000, s81
	v_add_u32_e32 v243, s81, v221
	ds_read_b64_tr_b16 v[160:161], v242 offset:24576
	ds_read_b64_tr_b16 v[162:163], v242 offset:25088
	ds_read_b64_tr_b16 v[164:165], v242 offset:25600
	ds_read_b64_tr_b16 v[166:167], v242 offset:26112
	ds_read_b64_tr_b16 v[168:169], v242 offset:26624
	ds_read_b64_tr_b16 v[170:171], v242 offset:27136
	ds_read_b64_tr_b16 v[172:173], v242 offset:27648
	ds_read_b64_tr_b16 v[174:175], v242 offset:28160
	v_mfma_f32_32x32x16_bf16 v[32:47], v[128:131], v[96:99], 0
	v_add_f32_e32 v204, v204, v80
	v_add_f32_e32 v205, v205, v81
	v_add_f32_e32 v208, v208, v82
	v_add_f32_e32 v209, v209, v83
	v_cvt_pk_bf16_f32 v112, v80, v81
	v_cvt_pk_bf16_f32 v113, v82, v83
	v_mfma_f32_32x32x16_bf16 v[64:79], v[132:135], v[96:99], 0
	v_add_f32_e32 v204, v204, v84
	v_add_f32_e32 v205, v205, v85
	v_add_f32_e32 v208, v208, v86
	v_add_f32_e32 v209, v209, v87
	v_cvt_pk_bf16_f32 v114, v84, v85
	v_cvt_pk_bf16_f32 v115, v86, v87
	s_and_b64 vcc, exec, s[82:83]
	s_cbranch_vccz .Lge_mk
	s_add_i32 s96, s7, 3
	s_and_b32 s80, s96, 3
	s_lshl_b32 s81, s80, 13
	s_cmp_eq_u32 s80, 3
	s_cselect_b32 s81, 0xe000, s81
	s_add_i32 s81, s81, s100
	s_mov_b32 m0, s81
	s_nop 0
	global_load_lds_dwordx4 v[244:245], off
	v_lshl_add_u64 v[244:245], v[244:245], 0, s[98:99]
.Lge_mk:
	v_mfma_f32_32x32x16_bf16 v[32:47], v[136:139], v[100:103], v[32:47]
	v_add_f32_e32 v204, v204, v88
	v_add_f32_e32 v205, v205, v89
	v_add_f32_e32 v208, v208, v90
	v_add_f32_e32 v209, v209, v91
	v_cvt_pk_bf16_f32 v116, v88, v89
	v_cvt_pk_bf16_f32 v117, v90, v91
	v_mfma_f32_32x32x16_bf16 v[64:79], v[140:143], v[100:103], v[64:79]
	v_add_f32_e32 v204, v204, v92
	v_add_f32_e32 v205, v205, v93
	v_add_f32_e32 v208, v208, v94
	v_add_f32_e32 v209, v209, v95
	v_cvt_pk_bf16_f32 v118, v92, v93
	v_cvt_pk_bf16_f32 v119, v94, v95
	v_mfma_f32_32x32x16_bf16 v[32:47], v[144:147], v[104:107], v[32:47]
	v_add_f32_e32 v204, v204, v48
	v_add_f32_e32 v205, v205, v49
	v_add_f32_e32 v208, v208, v50
	v_add_f32_e32 v209, v209, v51
	v_cvt_pk_bf16_f32 v120, v48, v49
	v_cvt_pk_bf16_f32 v121, v50, v51
	v_mfma_f32_32x32x16_bf16 v[64:79], v[148:151], v[104:107], v[64:79]
	v_add_f32_e32 v204, v204, v52
	v_add_f32_e32 v205, v205, v53
	v_add_f32_e32 v208, v208, v54
	v_add_f32_e32 v209, v209, v55
	v_cvt_pk_bf16_f32 v122, v52, v53
	v_cvt_pk_bf16_f32 v123, v54, v55
	s_add_i32 s96, s7, 1
	s_cmp_lt_i32 s96, s71
	s_cbranch_scc0 .Lge_mv
	s_mul_hi_u32 s80, s96, 0x55555556
	s_mul_i32 s80, s80, 3
	s_sub_u32 s80, s96, s80
	s_lshl_b32 s81, s80, 13
	s_cmp_eq_u32 s80, 2
	s_cselect_b32 s81, 0x6000, s81
	s_add_i32 s81, s81, 0x6000
	s_add_i32 s81, s81, s100
	s_mov_b32 m0, s81
	s_nop 0
	global_load_lds_dwordx4 v[246:247], off
	v_lshl_add_u64 v[246:247], v[246:247], 0, s[98:99]
.Lge_mv:
	v_mfma_f32_32x32x16_bf16 v[32:47], v[152:155], v[108:111], v[32:47]
	v_add_f32_e32 v204, v204, v56
	v_add_f32_e32 v205, v205, v57
	v_add_f32_e32 v208, v208, v58
	v_add_f32_e32 v209, v209, v59
	v_cvt_pk_bf16_f32 v124, v56, v57
	v_cvt_pk_bf16_f32 v125, v58, v59
	v_mfma_f32_32x32x16_bf16 v[64:79], v[156:159], v[108:111], v[64:79]
	v_add_f32_e32 v204, v204, v60
	v_add_f32_e32 v205, v205, v61
	v_add_f32_e32 v208, v208, v62
	v_add_f32_e32 v209, v209, v63
	v_cvt_pk_bf16_f32 v126, v60, v61
	v_cvt_pk_bf16_f32 v127, v62, v63
	ds_read_b64_tr_b16 v[176:177], v242 offset:28672
	ds_read_b64_tr_b16 v[178:179], v242 offset:29184
	ds_read_b64_tr_b16 v[180:181], v242 offset:29696
	ds_read_b64_tr_b16 v[182:183], v242 offset:30208
	ds_read_b64_tr_b16 v[184:185], v242 offset:30720
	ds_read_b64_tr_b16 v[186:187], v242 offset:31232
	ds_read_b64_tr_b16 v[188:189], v242 offset:31744
	s_waitcnt lgkmcnt(14)
	ds_read_b64_tr_b16 v[190:191], v242 offset:32256
	s_waitcnt lgkmcnt(14)
	v_mfma_f32_32x32x16_bf16 v[0:15], v[160:163], v[112:115], v[0:15]
	v_exp_f32_e32 v32, v32
	v_exp_f32_e32 v33, v33
	v_exp_f32_e32 v34, v34
	v_exp_f32_e32 v35, v35
	s_waitcnt lgkmcnt(12)
	v_mfma_f32_32x32x16_bf16 v[0:15], v[164:167], v[116:119], v[0:15]
	v_exp_f32_e32 v36, v36
	v_exp_f32_e32 v37, v37
	v_exp_f32_e32 v38, v38
	v_exp_f32_e32 v39, v39
	s_waitcnt lgkmcnt(10)
	v_mfma_f32_32x32x16_bf16 v[0:15], v[168:171], v[120:123], v[0:15]
	v_exp_f32_e32 v40, v40
	v_exp_f32_e32 v41, v41
	v_exp_f32_e32 v42, v42
	v_exp_f32_e32 v43, v43
	ds_read_b128 v[128:131], v243
	ds_read_b128 v[132:135], v243 offset:512
	s_waitcnt lgkmcnt(10)
	v_mfma_f32_32x32x16_bf16 v[0:15], v[172:175], v[124:127], v[0:15]
	v_exp_f32_e32 v44, v44
	v_exp_f32_e32 v45, v45
	v_exp_f32_e32 v46, v46
	v_exp_f32_e32 v47, v47
	ds_read_b128 v[136:139], v243 offset:2048
	ds_read_b128 v[140:143], v243 offset:2560
	s_waitcnt lgkmcnt(10)
	v_mfma_f32_32x32x16_bf16 v[16:31], v[176:179], v[112:115], v[16:31]
	v_exp_f32_e32 v64, v64
	v_exp_f32_e32 v65, v65
	v_exp_f32_e32 v66, v66
	v_exp_f32_e32 v67, v67
	ds_read_b128 v[144:147], v243 offset:4096
	ds_read_b128 v[148:151], v243 offset:4608
	s_waitcnt lgkmcnt(10)
	v_mfma_f32_32x32x16_bf16 v[16:31], v[180:183], v[116:119], v[16:31]
	v_exp_f32_e32 v68, v68
	v_exp_f32_e32 v69, v69
	v_exp_f32_e32 v70, v70
	v_exp_f32_e32 v71, v71
	ds_read_b128 v[152:155], v243 offset:6144
	ds_read_b128 v[156:159], v243 offset:6656
	s_waitcnt lgkmcnt(10)
	v_mfma_f32_32x32x16_bf16 v[16:31], v[184:187], v[120:123], v[16:31]
	v_exp_f32_e32 v72, v72
	v_exp_f32_e32 v73, v73
	v_exp_f32_e32 v74, v74
	v_exp_f32_e32 v75, v75
	s_waitcnt lgkmcnt(8)
	v_mfma_f32_32x32x16_bf16 v[16:31], v[188:191], v[124:127], v[16:31]
	v_exp_f32_e32 v76, v76
	v_exp_f32_e32 v77, v77
	v_exp_f32_e32 v78, v78
	v_exp_f32_e32 v79, v79
	s_waitcnt lgkmcnt(0)
	s_and_b64 vcc, exec, s[82:83]
	s_cbranch_vccz .Lge_w0
	s_waitcnt vmcnt(2)
	s_branch .Lge_w1

; template <bool NOMAX> ...
;     ...
;         for (int t = 1; t < NF; t += 2) {
;             ATT_STEP(t, kreg, vreg, kregB, vregB, e0, e1, c0, c1);
;             if (t + 1 < NF) ATT_STEP(t + 1, kregB, vregB, kreg, vreg, c0, c1, e0, e1);
;         }
;         if ((NF - 1) & 1) { e0 = c0; e1 = c1; }
;     ...
;         { u32x4 pw[4]; float sacc = 0.f;
; #pragma unroll
;           for (int r = 0; r < 16; ++r) sacc += e0[r] + e1[r];
;           lsum += sacc;
.Lg_done:
	v_add_f32_e32 v204, v204, v205
	v_add_f32_e32 v208, v208, v209
	v_add_f32_e32 v124, v204, v208
	s_waitcnt lgkmcnt(0)
	s_barrier
	s_branch .LBB0_535
	s_nop 0
	s_nop 0
	s_nop 0
	s_nop 0
	s_nop 0
	s_nop 0
	s_nop 0
	s_nop 0
	s_nop 0
	s_nop 0
	s_nop 0
	s_nop 0
	s_nop 0
	s_nop 0
	s_nop 0
	s_nop 0
	s_nop 0
	s_nop 0
	s_nop 0
	s_nop 0
	s_nop 0
	s_nop 0
	s_nop 0
	s_nop 0
	s_nop 0
	s_nop 0
	s_nop 0
	s_nop 0
	s_nop 0
	s_nop 0
	s_nop 0
	s_nop 0
	s_nop 0
	s_nop 0
	s_nop 0
	s_nop 0
	s_nop 0
	s_nop 0
	s_nop 0
	s_nop 0
	s_nop 0
	s_nop 0
	s_nop 0
	s_nop 0
	s_nop 0
	s_nop 0
	s_nop 0
	s_nop 0
	s_nop 0
	s_nop 0
	s_nop 0
	s_nop 0
